# P13 unit order 4 token tiles x 8 column tiles per XCD round (hidden activations streamed once per XCD)
# speedup vs baseline: 1.0029x; 1.0029x over previous
.LBB0_1531:
	s_cmp_lt_i32 s74, 14
	s_cselect_b64 s[4:5], -1, 0
	s_and_b64 s[6:7], s[4:5], s[0:1]
	s_andn2_b64 vcc, exec, s[6:7]
	s_cbranch_vccnz .LBB0_1570
	s_and_b32 s4, s78, 0xffffffc0
	s_cmpk_lt_i32 s2, 0x400
	s_cselect_b64 s[0:1], -1, 0
	s_add_i32 s5, 0, 0x250a8
	v_mov_b32_e32 v0, s5
	ds_read_b64 v[2:3], v0
	v_mbcnt_lo_u32_b32 v0, -1, 0
	v_mbcnt_hi_u32_b32 v8, -1, v0
	v_add_u32_e32 v0, s4, v8
	s_and_b64 vcc, exec, s[0:1]
	s_waitcnt lgkmcnt(0)
	v_readfirstlane_b32 s5, v3
	v_readfirstlane_b32 s14, v2
	v_readfirstlane_b32 s4, v0
	s_cbranch_vccz .LBB0_1534
	s_ashr_i32 s8, s2, 31
	s_lshr_b32 s8, s8, 29
	s_add_i32 s8, s2, s8
	s_ashr_i32 s9, s8, 3
	s_and_b32 s8, s8, -8
	s_sub_i32 s8, s2, s8
	s_lshl_b32 s11, s8, 7
	s_mul_i32 s10, s8, 0x81
	s_cmp_lt_i32 s8, 0
	s_cselect_b32 s8, s10, s11
	s_add_i32 s8, s8, s9
	s_lshr_b32 s10, s8, 5
	s_lshl_b32 s10, s10, 2
	s_and_b32 s9, s8, 31
	s_lshr_b32 s42, s9, 2
	s_and_b32 s9, s9, 3
	s_add_i32 s44, s10, s9

.LBB0_1545:
	s_ashr_i32 s34, s36, 3
	s_add_i32 s34, s38, s34
	s_lshr_b32 s36, s34, 5
	s_lshl_b32 s36, s36, 2
	s_and_b32 s35, s34, 31
	s_lshr_b32 s34, s35, 2
	s_and_b32 s35, s35, 3
	s_add_i32 s36, s36, s35
